# P9 K-split tail units run only the first half of the epilogue (second-half owner keeps its sums in the first-half registers, row base + 128)
# speedup vs baseline: 1.0033x; 1.0033x over previous
;     __device__ __forceinline__ void operator()(const f32x4 (&acc)[2][2][4][2], const Unit& u, int wr, int wc, int fr, int fq) const {
;         const int col0 = u.pn * BM + wc * 32 + 4 * fq;
; #pragma unroll
;         for (int ai = 0; ai < 2; ++ai) {
;             const int grb = row_base + u.pm * BM + ai * HALF + wr * 64;
;             const int seq = grb < MP ? (grb >> 11) : NPB + ((grb - MP) >> 6);
;             const float* gp = gate + (size_t)seq * (6 * DM) + col0;
;             f32x4 gv[2][2];
; #pragma unroll
;             for (int bj = 0; bj < 2; ++bj)
; #pragma unroll
;                 for (int n = 0; n < 2; ++n) gv[bj][n] = *(const f32x4*)(gp + bj * HALF + n * 16);
;             if (u.part == 0) {
; #pragma unroll
;                 for (int mp = 0; mp < 2; ++mp) {
;                 f32x4 xv[2][2][2];
; #pragma unroll
;                 for (int mm = 0; mm < 2; ++mm) { const int gr = grb + (2 * mp + mm) * 16 + fr;
;                     const float* xr = (gr < MP ? xin_p + (size_t)gr * DM : xin_s + (size_t)(gr - MP) * DM) + col0;
; #pragma unroll
;                     for (int bj = 0; bj < 2; ++bj)
; #pragma unroll
;                         for (int n = 0; n < 2; ++n) xv[mm][bj][n] = *(const f32x4*)(xr + bj * HALF + n * 16); }
.Lks9_recv1:
	global_load_dwordx4 v[66:69], v131, s[12:13] sc0 sc1
	v_add_u32_e32 v131, 0x2000, v131
	global_load_dwordx4 v[70:73], v131, s[12:13] sc0 sc1
	v_add_u32_e32 v131, 0x2000, v131
	global_load_dwordx4 v[74:77], v131, s[12:13] sc0 sc1
	v_add_u32_e32 v131, 0x2000, v131
	global_load_dwordx4 v[78:81], v131, s[12:13] sc0 sc1
	v_add_u32_e32 v131, 0x2000, v131
	global_load_dwordx4 v[82:85], v131, s[12:13] sc0 sc1
	v_add_u32_e32 v131, 0x2000, v131
	global_load_dwordx4 v[86:89], v131, s[12:13] sc0 sc1
	v_add_u32_e32 v131, 0x2000, v131
	global_load_dwordx4 v[90:93], v131, s[12:13] sc0 sc1
	v_add_u32_e32 v131, 0x2000, v131
	global_load_dwordx4 v[94:97], v131, s[12:13] sc0 sc1
	v_add_u32_e32 v131, 0x2000, v131
	global_load_dwordx4 v[98:101], v131, s[12:13] sc0 sc1
	v_add_u32_e32 v131, 0x2000, v131
	global_load_dwordx4 v[102:105], v131, s[12:13] sc0 sc1
	v_add_u32_e32 v131, 0x2000, v131
	global_load_dwordx4 v[106:109], v131, s[12:13] sc0 sc1
	v_add_u32_e32 v131, 0x2000, v131
	global_load_dwordx4 v[110:113], v131, s[12:13] sc0 sc1
	v_add_u32_e32 v131, 0x2000, v131
	global_load_dwordx4 v[114:117], v131, s[12:13] sc0 sc1
	v_add_u32_e32 v131, 0x2000, v131
	global_load_dwordx4 v[118:121], v131, s[12:13] sc0 sc1
	v_add_u32_e32 v131, 0x2000, v131
	global_load_dwordx4 v[122:125], v131, s[12:13] sc0 sc1
	v_add_u32_e32 v131, 0x2000, v131
	global_load_dwordx4 v[126:129], v131, s[12:13] sc0 sc1
	v_add_u32_e32 v131, 0x2000, v131
	s_waitcnt vmcnt(15)
	v_pk_add_f32 v[66:67], v[2:3], v[66:67]
	v_pk_add_f32 v[68:69], v[4:5], v[68:69]
	s_waitcnt vmcnt(14)
	v_pk_add_f32 v[70:71], v[6:7], v[70:71]
	v_pk_add_f32 v[72:73], v[8:9], v[72:73]
	s_waitcnt vmcnt(13)
	v_pk_add_f32 v[74:75], v[10:11], v[74:75]
	v_pk_add_f32 v[76:77], v[12:13], v[76:77]
	s_waitcnt vmcnt(12)
	v_pk_add_f32 v[78:79], v[14:15], v[78:79]
	v_pk_add_f32 v[80:81], v[16:17], v[80:81]
	s_waitcnt vmcnt(11)
	v_pk_add_f32 v[82:83], v[18:19], v[82:83]
	v_pk_add_f32 v[84:85], v[20:21], v[84:85]
	s_waitcnt vmcnt(10)
	v_pk_add_f32 v[86:87], v[22:23], v[86:87]
	v_pk_add_f32 v[88:89], v[24:25], v[88:89]
	s_waitcnt vmcnt(9)
	v_pk_add_f32 v[90:91], v[26:27], v[90:91]
	v_pk_add_f32 v[92:93], v[28:29], v[92:93]
	s_waitcnt vmcnt(8)
	v_pk_add_f32 v[94:95], v[30:31], v[94:95]
	v_pk_add_f32 v[96:97], v[32:33], v[96:97]
	s_waitcnt vmcnt(7)
	v_pk_add_f32 v[98:99], v[34:35], v[98:99]
	v_pk_add_f32 v[100:101], v[36:37], v[100:101]
	s_waitcnt vmcnt(6)
	v_pk_add_f32 v[102:103], v[38:39], v[102:103]
	v_pk_add_f32 v[104:105], v[40:41], v[104:105]
	s_waitcnt vmcnt(5)
	v_pk_add_f32 v[106:107], v[42:43], v[106:107]
	v_pk_add_f32 v[108:109], v[44:45], v[108:109]
	s_waitcnt vmcnt(4)
	v_pk_add_f32 v[110:111], v[46:47], v[110:111]
	v_pk_add_f32 v[112:113], v[48:49], v[112:113]
	s_waitcnt vmcnt(3)
	v_pk_add_f32 v[114:115], v[50:51], v[114:115]
	v_pk_add_f32 v[116:117], v[52:53], v[116:117]
	s_waitcnt vmcnt(2)
	v_pk_add_f32 v[118:119], v[54:55], v[118:119]
	v_pk_add_f32 v[120:121], v[56:57], v[120:121]
	s_waitcnt vmcnt(1)
	v_pk_add_f32 v[122:123], v[58:59], v[122:123]
	v_pk_add_f32 v[124:125], v[60:61], v[124:125]
	s_waitcnt vmcnt(0)
	v_pk_add_f32 v[126:127], v[62:63], v[126:127]
	v_pk_add_f32 v[128:129], v[64:65], v[128:129]
.Lks9_done:
	s_lshl_b32 s22, s48, 8
	s_add_i32 s22, s22, s42
	s_cmp_eq_u32 s100, 2
	s_cselect_b32 s21, 0x80, 0
	s_or_b32 s22, s22, s21
	s_add_i32 s21, s22, 0xffff8000
	s_lshr_b32 s21, s21, 6
	s_ashr_i32 s20, s22, 11
	s_add_i32 s21, s21, 16
	s_cmp_lt_i32 s22, 0x8000
	s_cselect_b32 s20, s20, s21
	v_lshl_or_b32 v130, s49, 8, v191
	s_mul_hi_i32 s21, s20, 0x6000
	s_mulk_i32 s20, 0x6000
	v_ashrrev_i32_e32 v131, 31, v130
	s_add_u32 s20, s40, s20
	s_addc_u32 s21, s41, s21
	v_lshlrev_b64 v[180:181], 2, v[130:131]
	v_lshl_add_u64 v[130:131], s[20:21], 0, v[180:181]
	v_or_b32_e32 v182, s22, v169
	s_mov_b32 s20, 0x8000
	v_readlane_b32 s34, v255, 0
	v_add_u32_e32 v0, 0xffff8000, v182
	v_cmp_gt_i32_e32 vcc, s20, v182
	v_readlane_b32 s35, v255, 1
	v_ashrrev_i32_e32 v183, 31, v182
	v_cndmask_b32_e32 v146, v0, v182, vcc
	v_mov_b32_e32 v0, s35
	v_mov_b32_e32 v148, s25
	v_cndmask_b32_e32 v147, 0, v183, vcc
	v_cndmask_b32_e32 v149, v0, v148, vcc
	v_mov_b32_e32 v0, s34
	v_mov_b32_e32 v148, s24
	v_cndmask_b32_e32 v148, v0, v148, vcc
	v_lshlrev_b64 v[146:147], 12, v[146:147]
	v_lshl_add_u64 v[146:147], v[148:149], 0, v[146:147]
	v_lshl_add_u64 v[146:147], v[146:147], 0, v[180:181]
	global_load_dwordx4 v[142:145], v[130:131], off
	global_load_dwordx4 v[138:141], v[130:131], off offset:64
	global_load_dwordx4 v[134:137], v[130:131], off offset:512
	s_nop 0
	global_load_dwordx4 v[130:133], v[130:131], off offset:576
	s_nop 0
	global_load_dwordx4 v[158:161], v[146:147], off
	global_load_dwordx4 v[154:157], v[146:147], off offset:64
	global_load_dwordx4 v[150:153], v[146:147], off offset:512
	s_nop 0
	global_load_dwordx4 v[146:149], v[146:147], off offset:576
	v_or_b32_e32 v186, 16, v182
	s_movk_i32 s20, 0x7fff
	v_cmp_lt_i32_e32 vcc, s20, v186
	s_and_saveexec_b64 s[20:21], vcc
	s_xor_b64 s[20:21], exec, s[20:21]
	v_add_u32_e32 v0, 0xffff8010, v182
	v_lshlrev_b64 v[184:185], 12, v[0:1]
	v_mov_b32_e32 v187, v1
	v_lshl_add_u64 v[188:189], s[34:35], 0, v[184:185]
	v_lshlrev_b64 v[184:185], 12, v[186:187]
	s_andn2_saveexec_b64 s[20:21], s[20:21]
	v_ashrrev_i32_e32 v187, 31, v186
	v_lshlrev_b64 v[184:185], 12, v[186:187]
	v_lshl_add_u64 v[188:189], s[24:25], 0, v[184:185]
	s_or_b64 exec, exec, s[20:21]
	v_lshl_add_u64 v[194:195], v[188:189], 0, v[180:181]
	global_load_dwordx4 v[186:189], v[194:195], off
	global_load_dwordx4 v[216:219], v[194:195], off offset:64
	global_load_dwordx4 v[220:223], v[194:195], off offset:512
	global_load_dwordx4 v[224:227], v[194:195], off offset:576
	v_lshlrev_b64 v[194:195], 12, v[182:183]
	s_waitcnt vmcnt(0)
;     __device__ __forceinline__ void operator()(const f32x4 (&acc)[2][2][4][2], const Unit& u, int wr, int wc, int fr, int fq) const {
;     ...
;                 for (int mm = 0; mm < 2; ++mm) { const int gr = grb + (2 * mp + mm) * 16 + fr;
;                     const float* xr = (gr < MP ? xin_p + (size_t)gr * DM : xin_s + (size_t)(gr - MP) * DM) + col0;
; #pragma unroll
;                     for (int bj = 0; bj < 2; ++bj)
; #pragma unroll
;                         for (int n = 0; n < 2; ++n) xv[mm][bj][n] = *(const f32x4*)(xr + bj * HALF + n * 16); }
; #pragma unroll
;                 for (int mm = 0; mm < 2; ++mm) { const int m = 2 * mp + mm; const int gr = grb + m * 16 + fr; float* orow = out + (size_t)gr * DM + col0;
; #pragma unroll
;                     for (int bj = 0; bj < 2; ++bj)
; #pragma unroll
;                         for (int n = 0; n < 2; ++n) *(f32x4*)(orow + bj * HALF + n * 16) = xv[mm][bj][n] + gv[bj][n] * acc[ai][bj][m][n]; }
	v_pk_fma_f32 v[146:147], v[114:115], v[130:131], v[146:147]
	v_or_b32_e32 v114, 32, v182
	s_mov_b32 s20, 0x8000
	v_pk_fma_f32 v[118:119], v[118:119], v[134:135], v[150:151]
	v_add_u32_e32 v0, 0xffff8020, v182
	v_lshl_add_u64 v[150:151], s[24:25], 0, v[194:195]
	v_ashrrev_i32_e32 v115, 31, v114
	v_cmp_gt_i32_e32 vcc, s20, v114
	v_pk_fma_f32 v[128:129], v[128:129], v[144:145], v[160:161]
	v_pk_fma_f32 v[126:127], v[126:127], v[142:143], v[158:159]
	v_pk_fma_f32 v[124:125], v[124:125], v[140:141], v[156:157]
	v_pk_fma_f32 v[122:123], v[122:123], v[138:139], v[154:155]
	v_pk_fma_f32 v[120:121], v[120:121], v[136:137], v[152:153]
	v_mov_b32_e32 v154, s35
	v_mov_b32_e32 v155, s25
	v_mov_b32_e32 v156, s34
	v_mov_b32_e32 v157, s24
	v_lshl_add_u64 v[150:151], v[150:151], 0, v[180:181]
	v_cndmask_b32_e32 v153, 0, v115, vcc
	v_cndmask_b32_e32 v152, v0, v114, vcc
	v_pk_fma_f32 v[148:149], v[116:117], v[132:133], v[148:149]
	v_lshl_add_u64 v[116:117], s[24:25], 0, v[184:185]
	v_cndmask_b32_e32 v155, v154, v155, vcc
	v_cndmask_b32_e32 v154, v156, v157, vcc
	global_store_dwordx4 v[150:151], v[126:129], off
	global_store_dwordx4 v[150:151], v[122:125], off offset:64
	global_store_dwordx4 v[150:151], v[118:121], off offset:512
	global_store_dwordx4 v[150:151], v[146:149], off offset:576
	v_lshl_add_u64 v[116:117], v[116:117], 0, v[180:181]
	v_lshlrev_b64 v[118:119], 12, v[152:153]
	v_lshl_add_u64 v[118:119], v[154:155], 0, v[118:119]
	v_lshl_add_u64 v[118:119], v[118:119], 0, v[180:181]
	s_movk_i32 s20, 0x7fff
	v_pk_fma_f32 v[112:113], v[112:113], v[144:145], v[188:189]
	v_pk_fma_f32 v[110:111], v[110:111], v[142:143], v[186:187]
	v_pk_fma_f32 v[108:109], v[108:109], v[140:141], v[218:219]
	v_pk_fma_f32 v[106:107], v[106:107], v[138:139], v[216:217]
	v_pk_fma_f32 v[104:105], v[104:105], v[136:137], v[222:223]
	v_pk_fma_f32 v[102:103], v[102:103], v[134:135], v[220:221]
	v_pk_fma_f32 v[100:101], v[100:101], v[132:133], v[226:227]
	v_pk_fma_f32 v[98:99], v[98:99], v[130:131], v[224:225]
	global_store_dwordx4 v[116:117], v[110:113], off
	global_store_dwordx4 v[116:117], v[106:109], off offset:64
	global_store_dwordx4 v[116:117], v[102:105], off offset:512
	global_store_dwordx4 v[116:117], v[98:101], off offset:576
	global_load_dwordx4 v[110:113], v[118:119], off
	s_nop 0
	global_load_dwordx4 v[106:109], v[118:119], off offset:64
	global_load_dwordx4 v[102:105], v[118:119], off offset:512
	global_load_dwordx4 v[98:101], v[118:119], off offset:576
	v_or_b32_e32 v118, 48, v182
	v_cmp_lt_i32_e32 vcc, s20, v118
	s_and_saveexec_b64 s[20:21], vcc
	s_xor_b64 s[20:21], exec, s[20:21]
	v_add_u32_e32 v0, 0xffff8030, v182
	v_lshlrev_b64 v[116:117], 12, v[0:1]
	v_mov_b32_e32 v119, v1
	v_lshl_add_u64 v[120:121], s[34:35], 0, v[116:117]
	v_lshlrev_b64 v[116:117], 12, v[118:119]
	s_andn2_saveexec_b64 s[20:21], s[20:21]
	v_ashrrev_i32_e32 v119, 31, v118
	v_lshlrev_b64 v[116:117], 12, v[118:119]
	v_lshl_add_u64 v[120:121], s[24:25], 0, v[116:117]
	s_or_b64 exec, exec, s[20:21]
	v_lshl_add_u64 v[146:147], v[120:121], 0, v[180:181]
	global_load_dwordx4 v[118:121], v[146:147], off
	global_load_dwordx4 v[122:125], v[146:147], off offset:64
	global_load_dwordx4 v[126:129], v[146:147], off offset:512
	s_nop 0
	global_load_dwordx4 v[146:149], v[146:147], off offset:576
	s_add_i32 s20, s22, 0x80
	s_addk_i32 s22, 0x8080
	s_lshr_b32 s22, s22, 6
	v_lshlrev_b64 v[114:115], 12, v[114:115]
	s_waitcnt vmcnt(4)
	v_pk_fma_f32 v[82:83], v[82:83], v[130:131], v[98:99]
	v_lshl_add_u64 v[98:99], s[24:25], 0, v[116:117]
	s_ashr_i32 s21, s20, 11
	s_add_i32 s22, s22, 16
	v_pk_fma_f32 v[86:87], v[86:87], v[134:135], v[102:103]
	v_pk_fma_f32 v[84:85], v[84:85], v[132:133], v[100:101]
	v_lshl_add_u64 v[100:101], s[24:25], 0, v[114:115]
	v_lshl_add_u64 v[102:103], v[98:99], 0, v[180:181]
	v_or_b32_e32 v98, s20, v169
	s_cmp_lt_i32 s20, 0x8000
	s_mov_b32 s20, 0x8000
	v_pk_fma_f32 v[96:97], v[96:97], v[144:145], v[112:113]
	v_pk_fma_f32 v[94:95], v[94:95], v[142:143], v[110:111]
	v_pk_fma_f32 v[90:91], v[90:91], v[138:139], v[106:107]
	v_lshl_add_u64 v[100:101], v[100:101], 0, v[180:181]
	v_ashrrev_i32_e32 v99, 31, v98
	v_add_u32_e32 v107, 0xffff8000, v98
	v_cmp_gt_i32_e32 vcc, s20, v98
	s_cselect_b32 s20, s21, s22
	v_pk_fma_f32 v[92:93], v[92:93], v[140:141], v[108:109]
	v_pk_fma_f32 v[88:89], v[88:89], v[136:137], v[104:105]
	v_mov_b32_e32 v0, s35
	v_mov_b32_e32 v104, s25
	v_mov_b32_e32 v105, s34
	v_mov_b32_e32 v106, s24
	global_store_dwordx4 v[100:101], v[94:97], off
	global_store_dwordx4 v[100:101], v[90:93], off offset:64
	global_store_dwordx4 v[100:101], v[86:89], off offset:512
	global_store_dwordx4 v[100:101], v[82:85], off offset:576
	s_mul_hi_i32 s21, s20, 0x6000
	s_mulk_i32 s20, 0x6000
	v_cndmask_b32_e32 v83, 0, v99, vcc
	v_cndmask_b32_e32 v82, v107, v98, vcc
	v_cndmask_b32_e32 v85, v0, v104, vcc
	v_cndmask_b32_e32 v84, v105, v106, vcc
	v_lshlrev_b64 v[82:83], 12, v[82:83]
	s_add_u32 s20, s40, s20
	v_lshl_add_u64 v[82:83], v[84:85], 0, v[82:83]
	s_addc_u32 s21, s41, s21
	v_lshl_add_u64 v[82:83], v[82:83], 0, v[180:181]
	v_lshl_add_u64 v[84:85], s[20:21], 0, v[180:181]
	s_movk_i32 s20, 0x7fff
	s_waitcnt vmcnt(7)
	v_pk_fma_f32 v[80:81], v[80:81], v[144:145], v[120:121]
	v_pk_fma_f32 v[78:79], v[78:79], v[142:143], v[118:119]
	s_waitcnt vmcnt(6)
	v_pk_fma_f32 v[76:77], v[76:77], v[140:141], v[124:125]
	v_pk_fma_f32 v[74:75], v[74:75], v[138:139], v[122:123]
	s_waitcnt vmcnt(5)
	v_pk_fma_f32 v[72:73], v[72:73], v[136:137], v[128:129]
	v_pk_fma_f32 v[70:71], v[70:71], v[134:135], v[126:127]
	s_waitcnt vmcnt(4)
	v_pk_fma_f32 v[68:69], v[68:69], v[132:133], v[148:149]
	v_pk_fma_f32 v[66:67], v[66:67], v[130:131], v[146:147]
	global_store_dwordx4 v[102:103], v[78:81], off
	global_store_dwordx4 v[102:103], v[74:77], off offset:64
	global_store_dwordx4 v[102:103], v[70:73], off offset:512
	global_store_dwordx4 v[102:103], v[66:69], off offset:576
	s_cmp_eq_u32 s100, 0
	s_cbranch_scc1 .Lks9_cont
	s_waitcnt vmcnt(0)
	s_and_b64 vcc, exec, s[4:5]
	s_mov_b64 s[4:5], -1
	s_branch .Lks9_end
;     __device__ __forceinline__ void operator()(const f32x4 (&acc)[2][2][4][2], const Unit& u, int wr, int wc, int fr, int fq) const {
;     ...
;                 for (int mp = 0; mp < 2; ++mp) {
;                 f32x4 xv[2][2][2];
; #pragma unroll
;                 for (int mm = 0; mm < 2; ++mm) { const int gr = grb + (2 * mp + mm) * 16 + fr;
;                     const float* xr = (gr < MP ? xin_p + (size_t)gr * DM : xin_s + (size_t)(gr - MP) * DM) + col0;
; #pragma unroll
;                     for (int bj = 0; bj < 2; ++bj)
; #pragma unroll
;                         for (int n = 0; n < 2; ++n) xv[mm][bj][n] = *(const f32x4*)(xr + bj * HALF + n * 16); }
; #pragma unroll
;                 for (int mm = 0; mm < 2; ++mm) { const int m = 2 * mp + mm; const int gr = grb + m * 16 + fr; float* orow = out + (size_t)gr * DM + col0;
; #pragma unroll
;                     for (int bj = 0; bj < 2; ++bj)
; #pragma unroll
;                         for (int n = 0; n < 2; ++n) *(f32x4*)(orow + bj * HALF + n * 16) = xv[mm][bj][n] + gv[bj][n] * acc[ai][bj][m][n]; }
;                 }
.Lks9_cont:
	global_load_dwordx4 v[78:81], v[84:85], off
	s_nop 0
	global_load_dwordx4 v[74:77], v[84:85], off offset:64
	global_load_dwordx4 v[70:73], v[84:85], off offset:512
	global_load_dwordx4 v[66:69], v[84:85], off offset:576
	global_load_dwordx4 v[94:97], v[82:83], off
	global_load_dwordx4 v[90:93], v[82:83], off offset:64
	global_load_dwordx4 v[86:89], v[82:83], off offset:512
	s_nop 0
	global_load_dwordx4 v[82:85], v[82:83], off offset:576
	v_or_b32_e32 v102, 16, v98
	v_cmp_lt_i32_e32 vcc, s20, v102
	s_and_saveexec_b64 s[20:21], vcc
	s_xor_b64 s[20:21], exec, s[20:21]
	v_add_u32_e32 v0, 0xffff8010, v98
	v_lshlrev_b64 v[100:101], 12, v[0:1]
	v_mov_b32_e32 v103, v1
	v_lshl_add_u64 v[104:105], s[34:35], 0, v[100:101]
	v_lshlrev_b64 v[100:101], 12, v[102:103]
	s_andn2_saveexec_b64 s[20:21], s[20:21]
	v_ashrrev_i32_e32 v103, 31, v102
	v_lshlrev_b64 v[100:101], 12, v[102:103]
	v_lshl_add_u64 v[104:105], s[24:25], 0, v[100:101]
	s_or_b64 exec, exec, s[20:21]
	v_lshl_add_u64 v[114:115], v[104:105], 0, v[180:181]
	global_load_dwordx4 v[102:105], v[114:115], off
	global_load_dwordx4 v[106:109], v[114:115], off offset:64
	global_load_dwordx4 v[110:113], v[114:115], off offset:512
	s_nop 0
	global_load_dwordx4 v[114:117], v[114:115], off offset:576
	v_lshlrev_b64 v[118:119], 12, v[98:99]
	s_waitcnt vmcnt(4)
	v_pk_fma_f32 v[82:83], v[50:51], v[66:67], v[82:83]
	v_or_b32_e32 v50, 32, v98
	s_mov_b32 s20, 0x8000
	v_pk_fma_f32 v[54:55], v[54:55], v[70:71], v[86:87]
	v_add_u32_e32 v0, 0xffff8020, v98
	v_lshl_add_u64 v[86:87], s[24:25], 0, v[118:119]
	v_ashrrev_i32_e32 v51, 31, v50
	v_cmp_gt_i32_e32 vcc, s20, v50
	v_pk_fma_f32 v[64:65], v[64:65], v[80:81], v[96:97]
	v_pk_fma_f32 v[62:63], v[62:63], v[78:79], v[94:95]
	v_pk_fma_f32 v[60:61], v[60:61], v[76:77], v[92:93]
	v_pk_fma_f32 v[58:59], v[58:59], v[74:75], v[90:91]
	v_pk_fma_f32 v[56:57], v[56:57], v[72:73], v[88:89]
	v_mov_b32_e32 v90, s35
	v_mov_b32_e32 v91, s25
	v_mov_b32_e32 v92, s34
	v_mov_b32_e32 v93, s24
	v_lshl_add_u64 v[86:87], v[86:87], 0, v[180:181]
	v_cndmask_b32_e32 v89, 0, v51, vcc
	v_cndmask_b32_e32 v88, v0, v50, vcc
	v_pk_fma_f32 v[84:85], v[52:53], v[68:69], v[84:85]
	v_lshl_add_u64 v[52:53], s[24:25], 0, v[100:101]
	v_cndmask_b32_e32 v91, v90, v91, vcc
	v_cndmask_b32_e32 v90, v92, v93, vcc
	global_store_dwordx4 v[86:87], v[62:65], off
	global_store_dwordx4 v[86:87], v[58:61], off offset:64
	global_store_dwordx4 v[86:87], v[54:57], off offset:512
	global_store_dwordx4 v[86:87], v[82:85], off offset:576
	v_lshl_add_u64 v[52:53], v[52:53], 0, v[180:181]
	v_lshlrev_b64 v[54:55], 12, v[88:89]
	v_lshl_add_u64 v[54:55], v[90:91], 0, v[54:55]
	v_lshl_add_u64 v[54:55], v[54:55], 0, v[180:181]
	s_movk_i32 s20, 0x7fff
	s_waitcnt vmcnt(7)
	v_pk_fma_f32 v[48:49], v[48:49], v[80:81], v[104:105]
	v_pk_fma_f32 v[46:47], v[46:47], v[78:79], v[102:103]
	s_waitcnt vmcnt(6)
	v_pk_fma_f32 v[44:45], v[44:45], v[76:77], v[108:109]
	v_pk_fma_f32 v[42:43], v[42:43], v[74:75], v[106:107]
	s_waitcnt vmcnt(5)
	v_pk_fma_f32 v[40:41], v[40:41], v[72:73], v[112:113]
	v_pk_fma_f32 v[38:39], v[38:39], v[70:71], v[110:111]
	s_waitcnt vmcnt(4)
	v_pk_fma_f32 v[36:37], v[36:37], v[68:69], v[116:117]
	v_pk_fma_f32 v[34:35], v[34:35], v[66:67], v[114:115]
	global_store_dwordx4 v[52:53], v[46:49], off
	global_store_dwordx4 v[52:53], v[42:45], off offset:64
	global_store_dwordx4 v[52:53], v[38:41], off offset:512
	global_store_dwordx4 v[52:53], v[34:37], off offset:576
	global_load_dwordx4 v[46:49], v[54:55], off
	s_nop 0
	global_load_dwordx4 v[42:45], v[54:55], off offset:64
	global_load_dwordx4 v[38:41], v[54:55], off offset:512
	global_load_dwordx4 v[34:37], v[54:55], off offset:576
	v_or_b32_e32 v54, 48, v98
	v_cmp_lt_i32_e32 vcc, s20, v54
	s_and_saveexec_b64 s[20:21], vcc
	s_xor_b64 s[20:21], exec, s[20:21]
	v_add_u32_e32 v0, 0xffff8030, v98
	v_lshlrev_b64 v[52:53], 12, v[0:1]
	v_mov_b32_e32 v55, v1
	v_lshl_add_u64 v[56:57], s[34:35], 0, v[52:53]
	v_lshlrev_b64 v[52:53], 12, v[54:55]
	s_andn2_saveexec_b64 s[20:21], s[20:21]
	v_ashrrev_i32_e32 v55, 31, v54
	v_lshlrev_b64 v[52:53], 12, v[54:55]
	v_lshl_add_u64 v[56:57], s[24:25], 0, v[52:53]
	s_or_b64 exec, exec, s[20:21]
	v_lshl_add_u64 v[82:83], v[56:57], 0, v[180:181]
	global_load_dwordx4 v[54:57], v[82:83], off
	global_load_dwordx4 v[58:61], v[82:83], off offset:64
	global_load_dwordx4 v[62:65], v[82:83], off offset:512
	s_nop 0
	global_load_dwordx4 v[82:85], v[82:83], off offset:576
	v_lshlrev_b64 v[50:51], 12, v[50:51]
	s_waitcnt vmcnt(4)
	v_pk_fma_f32 v[20:21], v[20:21], v[68:69], v[36:37]
	v_pk_fma_f32 v[18:19], v[18:19], v[66:67], v[34:35]
	v_lshl_add_u64 v[34:35], s[24:25], 0, v[52:53]
	v_lshl_add_u64 v[36:37], s[24:25], 0, v[50:51]
	v_pk_fma_f32 v[32:33], v[32:33], v[80:81], v[48:49]
	v_pk_fma_f32 v[30:31], v[30:31], v[78:79], v[46:47]
	s_and_b64 vcc, exec, s[4:5]
	v_lshl_add_u64 v[34:35], v[34:35], 0, v[180:181]
	v_lshl_add_u64 v[36:37], v[36:37], 0, v[180:181]
	s_mov_b64 s[4:5], -1
	v_pk_fma_f32 v[28:29], v[28:29], v[76:77], v[44:45]
	v_pk_fma_f32 v[26:27], v[26:27], v[74:75], v[42:43]
	v_pk_fma_f32 v[24:25], v[24:25], v[72:73], v[40:41]
	v_pk_fma_f32 v[22:23], v[22:23], v[70:71], v[38:39]
	global_store_dwordx4 v[36:37], v[30:33], off
	global_store_dwordx4 v[36:37], v[26:29], off offset:64
	global_store_dwordx4 v[36:37], v[22:25], off offset:512
	global_store_dwordx4 v[36:37], v[18:21], off offset:576
	s_waitcnt vmcnt(7)
	v_pk_fma_f32 v[16:17], v[16:17], v[80:81], v[56:57]
	v_pk_fma_f32 v[14:15], v[14:15], v[78:79], v[54:55]
	s_waitcnt vmcnt(6)
	v_pk_fma_f32 v[12:13], v[12:13], v[76:77], v[60:61]
	v_pk_fma_f32 v[10:11], v[10:11], v[74:75], v[58:59]
	s_waitcnt vmcnt(5)
	v_pk_fma_f32 v[8:9], v[8:9], v[72:73], v[64:65]
	v_pk_fma_f32 v[6:7], v[6:7], v[70:71], v[62:63]
	s_waitcnt vmcnt(4)
	v_pk_fma_f32 v[4:5], v[4:5], v[68:69], v[84:85]
	v_pk_fma_f32 v[2:3], v[2:3], v[66:67], v[82:83]
	global_store_dwordx4 v[34:35], v[14:17], off
	global_store_dwordx4 v[34:35], v[10:13], off offset:64
	global_store_dwordx4 v[34:35], v[6:9], off offset:512
	global_store_dwordx4 v[34:35], v[2:5], off offset:576
.Lks9_end:
	s_cbranch_vccnz .LBB0_985
	s_andn2_b64 vcc, exec, s[8:9]
	s_cbranch_vccnz .LBB0_984
	s_barrier
	s_branch .LBB0_984
